# baseline (speedup 1.0000x reference)
; __device__ __forceinline__ void partialSM(f32x16& p0, f32x16& p1, float& m_reg, float& mn, float& alpha) {
;   constexpr float C = SCALE * 1.4426950408889634f;
;   float pmax = p0[0]; for (int r = 1; r < 16; ++r) pmax = fmaxf(pmax, p0[r]); for (int r = 0; r < 16; ++r) pmax = fmaxf(pmax, p1[r]);
;   { auto rr = __builtin_amdgcn_permlane32_swap(__float_as_uint(pmax), __float_as_uint(pmax), false, false);
;     pmax = fmaxf(__uint_as_float(rr[0]), __uint_as_float(rr[1])); }
;   if (__builtin_expect(__all(pmax - m_reg <= THR / SCALE), 1)) { mn = m_reg; alpha = 1.f; }
;   else { mn = fmaxf(m_reg, pmax); alpha = __builtin_amdgcn_exp2f((m_reg - mn) * C); m_reg = mn; }
; __device__ __forceinline__ void qkt(f32x16& p0, f32x16& p1, const bf16_t* Ks, const bf16x8* qr, int r32, int hi) {
;   p0 = f32x16{}; p1 = f32x16{};
;   for (int d0 = 0; d0 < 8; ++d0) { int cb = (d0 * 16 + hi * 8) * 2;
;     bf16x8 b0 = *reinterpret_cast<const bf16x8*>((const char*)Ks + KSWZ(r32, cb));
;     bf16x8 b1 = *reinterpret_cast<const bf16x8*>((const char*)Ks + KSWZ(32 + r32, cb));
;     p0 = __builtin_amdgcn_mfma_f32_32x32x16_bf16(b0, qr[d0], p0, 0, 0, 0);
;     p1 = __builtin_amdgcn_mfma_f32_32x32x16_bf16(b1, qr[d0], p1, 0, 0, 0); }
.Lat_x_top:
	s_add_i32 s8, s13, -2
	s_and_b32 s25, s8, 1
	s_lshl_b32 s24, s25, 14
	s_setprio 1
	s_waitcnt lgkmcnt(4)
	v_mfma_f32_16x16x32_bf16 v[130:133], v[194:197], v[162:165], 0
	v_mfma_f32_16x16x32_bf16 v[134:137], v[194:197], v[178:181], 0
	v_mfma_f32_16x16x32_bf16 v[138:141], v[198:201], v[162:165], 0
	v_mfma_f32_16x16x32_bf16 v[142:145], v[198:201], v[178:181], 0
	ds_read_b128 v[194:197], v247 offset:8192
	ds_read_b128 v[198:201], v247 offset:12288
	s_waitcnt lgkmcnt(4)
	v_mfma_f32_16x16x32_bf16 v[146:149], v[202:205], v[162:165], 0
	v_mfma_f32_16x16x32_bf16 v[150:153], v[202:205], v[178:181], 0
	v_mfma_f32_16x16x32_bf16 v[154:157], v[206:209], v[162:165], 0
	v_mfma_f32_16x16x32_bf16 v[158:161], v[206:209], v[178:181], 0
	ds_read_b128 v[202:205], v239
	ds_read_b128 v[206:209], v239 offset:4096
	s_waitcnt lgkmcnt(4)
	v_mfma_f32_16x16x32_bf16 v[130:133], v[210:213], v[166:169], v[130:133]
	v_mfma_f32_16x16x32_bf16 v[134:137], v[210:213], v[182:185], v[134:137]
	v_mfma_f32_16x16x32_bf16 v[138:141], v[214:217], v[166:169], v[138:141]
	v_mfma_f32_16x16x32_bf16 v[142:145], v[214:217], v[182:185], v[142:145]
	ds_read_b128 v[210:213], v239 offset:8192
	ds_read_b128 v[214:217], v239 offset:12288
	s_waitcnt lgkmcnt(4)
	v_mfma_f32_16x16x32_bf16 v[146:149], v[194:197], v[166:169], v[146:149]
	v_mfma_f32_16x16x32_bf16 v[150:153], v[194:197], v[182:185], v[150:153]
	v_mfma_f32_16x16x32_bf16 v[154:157], v[198:201], v[166:169], v[154:157]
	v_mfma_f32_16x16x32_bf16 v[158:161], v[198:201], v[182:185], v[158:161]
	ds_read_b128 v[194:197], v245
	ds_read_b128 v[198:201], v245 offset:4096
	s_waitcnt lgkmcnt(4)
	v_mfma_f32_16x16x32_bf16 v[130:133], v[202:205], v[170:173], v[130:133]
	v_mfma_f32_16x16x32_bf16 v[134:137], v[202:205], v[186:189], v[134:137]
	v_mfma_f32_16x16x32_bf16 v[138:141], v[206:209], v[170:173], v[138:141]
	v_mfma_f32_16x16x32_bf16 v[142:145], v[206:209], v[186:189], v[142:145]
	ds_read_b128 v[202:205], v245 offset:8192
	ds_read_b128 v[206:209], v245 offset:12288
	s_waitcnt lgkmcnt(4)
	v_mfma_f32_16x16x32_bf16 v[146:149], v[210:213], v[170:173], v[146:149]
	v_mfma_f32_16x16x32_bf16 v[150:153], v[210:213], v[186:189], v[150:153]
	v_mfma_f32_16x16x32_bf16 v[154:157], v[214:217], v[170:173], v[154:157]
	v_mfma_f32_16x16x32_bf16 v[158:161], v[214:217], v[186:189], v[158:161]
	s_waitcnt lgkmcnt(2)
	v_mfma_f32_16x16x32_bf16 v[130:133], v[194:197], v[174:177], v[130:133]
	v_mfma_f32_16x16x32_bf16 v[134:137], v[194:197], v[190:193], v[134:137]
	v_mfma_f32_16x16x32_bf16 v[138:141], v[198:201], v[174:177], v[138:141]
	v_mfma_f32_16x16x32_bf16 v[142:145], v[198:201], v[190:193], v[142:145]
	s_waitcnt lgkmcnt(0)
	v_mfma_f32_16x16x32_bf16 v[146:149], v[202:205], v[174:177], v[146:149]
	v_mfma_f32_16x16x32_bf16 v[150:153], v[202:205], v[190:193], v[150:153]
	v_mfma_f32_16x16x32_bf16 v[154:157], v[206:209], v[174:177], v[154:157]
	v_mfma_f32_16x16x32_bf16 v[158:161], v[206:209], v[190:193], v[158:161]
	s_setprio 0
	s_nop 6
	v_max3_f32 v194, v130, v131, v132
	v_max3_f32 v194, v194, v133, v138
	v_max3_f32 v194, v194, v139, v140
	v_max3_f32 v194, v194, v141, v146
	v_max3_f32 v194, v194, v147, v148
	v_max3_f32 v194, v194, v149, v154
	v_max3_f32 v194, v194, v155, v156
	v_max_f32_e32 v194, v194, v157
	v_max3_f32 v195, v134, v135, v136
	v_max3_f32 v195, v195, v137, v142
	v_max3_f32 v195, v195, v143, v144
	v_max3_f32 v195, v195, v145, v150
	v_max3_f32 v195, v195, v151, v152
	v_max3_f32 v195, v195, v153, v158
	v_max3_f32 v195, v195, v159, v160
	v_max_f32_e32 v195, v195, v161
	v_mov_b32_e32 v196, v194
	v_mov_b32_e32 v197, v195
	s_nop 1
	v_permlane32_swap_b32_e32 v194, v196
	v_permlane32_swap_b32_e32 v195, v197
	v_max_f32_e32 v194, v194, v196
	v_max_f32_e32 v195, v195, v197
	v_mov_b32_e32 v196, v194
	v_mov_b32_e32 v197, v195
	s_nop 1
	v_permlane16_swap_b32_e32 v194, v196
	v_permlane16_swap_b32_e32 v195, v197
	v_max_f32_e32 v194, v194, v196
	v_max_f32_e32 v195, v195, v197
	v_sub_f32_e32 v196, v194, v249
	v_sub_f32_e32 v197, v195, v246
	v_max_f32_e32 v196, v196, v197
	v_cmp_ge_f32_e32 vcc, 0x42b504f3, v196
	v_max_f32_e32 v198, v249, v194
	v_max_f32_e32 v199, v246, v195
	v_sub_f32_e32 v196, v249, v198
	v_sub_f32_e32 v197, v246, v199
	v_mul_f32_e32 v196, 0x3e0293ee, v196
	v_mul_f32_e32 v197, 0x3e0293ee, v197
	v_exp_f32_e32 v196, v196
	v_exp_f32_e32 v197, v197
	s_cmp_eq_u64 vcc, exec
	s_cselect_b64 s[8:9], -1, 0
	v_cndmask_b32_e64 v236, v196, 1.0, s[8:9]
	v_cndmask_b32_e64 v240, v197, 1.0, s[8:9]
	v_cndmask_b32_e64 v249, v198, v249, s[8:9]
	v_cndmask_b32_e64 v246, v199, v246, s[8:9]
	s_cbranch_scc1 .Lat_x_noresc
; __device__ __forceinline__ int crow(int r, int hi) { return (r & 3) + 8 * (r >> 2) + 4 * hi; }
; __device__ __forceinline__ int crow(int r, int hi) { return (r & 3) + 8 * (r >> 2) + 4 * hi; }
; __device__ __forceinline__ void partialSM(f32x16& p0, f32x16& p1, float& m_reg, float& mn, float& alpha) {
;     ...
;   float mnC = -mn * C;
;   for (int r = 0; r < 16; ++r) p0[r] = fmaf(p0[r], C, mnC); for (int r = 0; r < 16; ++r) p1[r] = fmaf(p1[r], C, mnC);
;   for (int r = 0; r < 16; ++r) p0[r] = __builtin_amdgcn_exp2f(p0[r]);
; __device__ __forceinline__ void attn_body256(const bf16_t* __restrict__ Qb, const bf16_t* __restrict__ Kh, const bf16_t* __restrict__ Vh,
;                                              bf16_t* Ob, int seq, unsigned char* lds, float lam, int MODE, bf16_t* Ab, const float* wsub) {
;     ...
;     if (__any(alpha < 1.f)) { if (hi == 0) al_l[r32] = alpha; asm volatile("s_waitcnt lgkmcnt(0)" ::: "memory");
; #pragma unroll
;       for (int r = 0; r < 16; ++r) { const float a = al_l[crow(r, hi)];
; #pragma unroll
;         for (int d = 0; d < 8; ++d) o[d][r] *= a; } }
	v_pk_mul_f32 v[2:3], v[2:3], v[236:237] op_sel_hi:[1,0]
	v_pk_mul_f32 v[4:5], v[4:5], v[236:237] op_sel_hi:[1,0]
	v_pk_mul_f32 v[6:7], v[6:7], v[240:241] op_sel_hi:[1,0]
	v_pk_mul_f32 v[8:9], v[8:9], v[240:241] op_sel_hi:[1,0]
	v_pk_mul_f32 v[10:11], v[10:11], v[236:237] op_sel_hi:[1,0]
	v_pk_mul_f32 v[12:13], v[12:13], v[236:237] op_sel_hi:[1,0]
	v_pk_mul_f32 v[14:15], v[14:15], v[240:241] op_sel_hi:[1,0]
	v_pk_mul_f32 v[16:17], v[16:17], v[240:241] op_sel_hi:[1,0]
	v_pk_mul_f32 v[114:115], v[114:115], v[236:237] op_sel_hi:[1,0]
	v_pk_mul_f32 v[116:117], v[116:117], v[236:237] op_sel_hi:[1,0]
	v_pk_mul_f32 v[118:119], v[118:119], v[240:241] op_sel_hi:[1,0]
	v_pk_mul_f32 v[120:121], v[120:121], v[240:241] op_sel_hi:[1,0]
	v_pk_mul_f32 v[122:123], v[122:123], v[236:237] op_sel_hi:[1,0]
	v_pk_mul_f32 v[124:125], v[124:125], v[236:237] op_sel_hi:[1,0]
	v_pk_mul_f32 v[126:127], v[126:127], v[240:241] op_sel_hi:[1,0]
	v_pk_mul_f32 v[128:129], v[128:129], v[240:241] op_sel_hi:[1,0]
	v_pk_mul_f32 v[98:99], v[98:99], v[236:237] op_sel_hi:[1,0]
	v_pk_mul_f32 v[100:101], v[100:101], v[236:237] op_sel_hi:[1,0]
	v_pk_mul_f32 v[102:103], v[102:103], v[240:241] op_sel_hi:[1,0]
	v_pk_mul_f32 v[104:105], v[104:105], v[240:241] op_sel_hi:[1,0]
	v_pk_mul_f32 v[106:107], v[106:107], v[236:237] op_sel_hi:[1,0]
	v_pk_mul_f32 v[108:109], v[108:109], v[236:237] op_sel_hi:[1,0]
	v_pk_mul_f32 v[110:111], v[110:111], v[240:241] op_sel_hi:[1,0]
	v_pk_mul_f32 v[112:113], v[112:113], v[240:241] op_sel_hi:[1,0]
	v_pk_mul_f32 v[82:83], v[82:83], v[236:237] op_sel_hi:[1,0]
	v_pk_mul_f32 v[84:85], v[84:85], v[236:237] op_sel_hi:[1,0]
	v_pk_mul_f32 v[86:87], v[86:87], v[240:241] op_sel_hi:[1,0]
	v_pk_mul_f32 v[88:89], v[88:89], v[240:241] op_sel_hi:[1,0]
	v_pk_mul_f32 v[90:91], v[90:91], v[236:237] op_sel_hi:[1,0]
	v_pk_mul_f32 v[92:93], v[92:93], v[236:237] op_sel_hi:[1,0]
	v_pk_mul_f32 v[94:95], v[94:95], v[240:241] op_sel_hi:[1,0]
	v_pk_mul_f32 v[96:97], v[96:97], v[240:241] op_sel_hi:[1,0]
	v_pk_mul_f32 v[66:67], v[66:67], v[236:237] op_sel_hi:[1,0]
	v_pk_mul_f32 v[68:69], v[68:69], v[236:237] op_sel_hi:[1,0]
	v_pk_mul_f32 v[70:71], v[70:71], v[240:241] op_sel_hi:[1,0]
	v_pk_mul_f32 v[72:73], v[72:73], v[240:241] op_sel_hi:[1,0]
	v_pk_mul_f32 v[74:75], v[74:75], v[236:237] op_sel_hi:[1,0]
	v_pk_mul_f32 v[76:77], v[76:77], v[236:237] op_sel_hi:[1,0]
	v_pk_mul_f32 v[78:79], v[78:79], v[240:241] op_sel_hi:[1,0]
	v_pk_mul_f32 v[80:81], v[80:81], v[240:241] op_sel_hi:[1,0]
	v_pk_mul_f32 v[50:51], v[50:51], v[236:237] op_sel_hi:[1,0]
	v_pk_mul_f32 v[52:53], v[52:53], v[236:237] op_sel_hi:[1,0]
	v_pk_mul_f32 v[54:55], v[54:55], v[240:241] op_sel_hi:[1,0]
	v_pk_mul_f32 v[56:57], v[56:57], v[240:241] op_sel_hi:[1,0]
	v_pk_mul_f32 v[58:59], v[58:59], v[236:237] op_sel_hi:[1,0]
	v_pk_mul_f32 v[60:61], v[60:61], v[236:237] op_sel_hi:[1,0]
	v_pk_mul_f32 v[62:63], v[62:63], v[240:241] op_sel_hi:[1,0]
	v_pk_mul_f32 v[64:65], v[64:65], v[240:241] op_sel_hi:[1,0]
	v_pk_mul_f32 v[34:35], v[34:35], v[236:237] op_sel_hi:[1,0]
	v_pk_mul_f32 v[36:37], v[36:37], v[236:237] op_sel_hi:[1,0]
	v_pk_mul_f32 v[38:39], v[38:39], v[240:241] op_sel_hi:[1,0]
	v_pk_mul_f32 v[40:41], v[40:41], v[240:241] op_sel_hi:[1,0]
	v_pk_mul_f32 v[42:43], v[42:43], v[236:237] op_sel_hi:[1,0]
	v_pk_mul_f32 v[44:45], v[44:45], v[236:237] op_sel_hi:[1,0]
	v_pk_mul_f32 v[46:47], v[46:47], v[240:241] op_sel_hi:[1,0]
	v_pk_mul_f32 v[48:49], v[48:49], v[240:241] op_sel_hi:[1,0]
	v_pk_mul_f32 v[18:19], v[18:19], v[236:237] op_sel_hi:[1,0]
	v_pk_mul_f32 v[20:21], v[20:21], v[236:237] op_sel_hi:[1,0]
	v_pk_mul_f32 v[22:23], v[22:23], v[240:241] op_sel_hi:[1,0]
	v_pk_mul_f32 v[24:25], v[24:25], v[240:241] op_sel_hi:[1,0]
	v_pk_mul_f32 v[26:27], v[26:27], v[236:237] op_sel_hi:[1,0]
	v_pk_mul_f32 v[28:29], v[28:29], v[236:237] op_sel_hi:[1,0]
	v_pk_mul_f32 v[30:31], v[30:31], v[240:241] op_sel_hi:[1,0]
	v_pk_mul_f32 v[32:33], v[32:33], v[240:241] op_sel_hi:[1,0]
.Lat_x_noresc:
	v_mul_f32_e32 v198, 0xbe0293ee, v249
	v_mul_f32_e32 v199, 0xbe0293ee, v246
	v_fmamk_f32 v130, v130, 0x3e0293ee, v198
	v_fmamk_f32 v131, v131, 0x3e0293ee, v198
	v_fmamk_f32 v132, v132, 0x3e0293ee, v198
	v_fmamk_f32 v133, v133, 0x3e0293ee, v198
	v_fmamk_f32 v134, v134, 0x3e0293ee, v199
	v_fmamk_f32 v135, v135, 0x3e0293ee, v199
	v_fmamk_f32 v136, v136, 0x3e0293ee, v199
	v_fmamk_f32 v137, v137, 0x3e0293ee, v199
	v_fmamk_f32 v138, v138, 0x3e0293ee, v198
	v_fmamk_f32 v139, v139, 0x3e0293ee, v198
	v_fmamk_f32 v140, v140, 0x3e0293ee, v198
	v_fmamk_f32 v141, v141, 0x3e0293ee, v198
	v_fmamk_f32 v142, v142, 0x3e0293ee, v199
	v_fmamk_f32 v143, v143, 0x3e0293ee, v199
	v_fmamk_f32 v144, v144, 0x3e0293ee, v199
	v_fmamk_f32 v145, v145, 0x3e0293ee, v199
	v_fmamk_f32 v146, v146, 0x3e0293ee, v198
	v_fmamk_f32 v147, v147, 0x3e0293ee, v198
	v_fmamk_f32 v148, v148, 0x3e0293ee, v198
	v_fmamk_f32 v149, v149, 0x3e0293ee, v198
	v_fmamk_f32 v150, v150, 0x3e0293ee, v199
	v_fmamk_f32 v151, v151, 0x3e0293ee, v199
	v_fmamk_f32 v152, v152, 0x3e0293ee, v199
	v_fmamk_f32 v153, v153, 0x3e0293ee, v199
	v_fmamk_f32 v154, v154, 0x3e0293ee, v198
	v_fmamk_f32 v155, v155, 0x3e0293ee, v198
	v_fmamk_f32 v156, v156, 0x3e0293ee, v198
	v_fmamk_f32 v157, v157, 0x3e0293ee, v198
	v_fmamk_f32 v158, v158, 0x3e0293ee, v199
	v_fmamk_f32 v159, v159, 0x3e0293ee, v199
	v_fmamk_f32 v160, v160, 0x3e0293ee, v199
	v_fmamk_f32 v161, v161, 0x3e0293ee, v199
	v_exp_f32_e32 v130, v130
	v_exp_f32_e32 v131, v131
	v_exp_f32_e32 v132, v132
	v_exp_f32_e32 v133, v133
	v_exp_f32_e32 v134, v134
	v_exp_f32_e32 v135, v135
	v_exp_f32_e32 v136, v136
	v_exp_f32_e32 v137, v137
	v_exp_f32_e32 v138, v138
	v_exp_f32_e32 v139, v139
; #define SBAR() __builtin_amdgcn_sched_barrier(0)
; #define PV_STEP(B) do { pv_reads<(B) + 1>(fn, vb); asm volatile("s_waitcnt lgkmcnt(8)" ::: "memory"); SBAR(); pv_mma(o[B], fc, pa0, pa1, pa2, pa3); SBAR(); fc = fn; } while (0)
; __device__ __forceinline__ void partialSM(f32x16& p0, f32x16& p1, float& m_reg, float& mn, float& alpha) {
;     ...
;   for (int r = 0; r < 16; ++r) p0[r] = __builtin_amdgcn_exp2f(p0[r]);
; }
; __device__ __forceinline__ void finishSM(f32x16& p0, f32x16& p1, float alpha, float& l_reg, bf16x8& pa0, bf16x8& pa1, bf16x8& pa2, bf16x8& pa3) {
;   for (int r = 0; r < 16; ++r) p1[r] = __builtin_amdgcn_exp2f(p1[r]);
;   float ps = 0; for (int r = 0; r < 16; ++r) ps += p0[r]; for (int r = 0; r < 16; ++r) ps += p1[r];
;   { auto rr = __builtin_amdgcn_permlane32_swap(__float_as_uint(ps), __float_as_uint(ps), false, false);
;     ps = __uint_as_float(rr[0]) + __uint_as_float(rr[1]); }
;   l_reg = l_reg * alpha + ps;
;     ...
;   PK4(p0, 0, pa0); PK4(p0, 8, pa1); PK4(p1, 0, pa2); PK4(p1, 8, pa3);
; template <int B> __device__ __forceinline__ void pv_reads(VFrag& f, int vb) {
;   constexpr int base = (B >> 2) * 16384 + (B & 3) * 512;
;   f.l0 = tr_read<base + 0 * 4096>(vb); f.h0 = tr_read<base + 0 * 4096 + 2048>(vb); f.l1 = tr_read<base + 1 * 4096>(vb); f.h1 = tr_read<base + 1 * 4096 + 2048>(vb);
;   f.l2 = tr_read<base + 2 * 4096>(vb); f.h2 = tr_read<base + 2 * 4096 + 2048>(vb); f.l3 = tr_read<base + 3 * 4096>(vb); f.h3 = tr_read<base + 3 * 4096 + 2048>(vb);
; }
; __device__ __forceinline__ void pv_mma(f32x16& od, const VFrag& f, bf16x8 pa0, bf16x8 pa1, bf16x8 pa2, bf16x8 pa3) {
;     ...
;   od = __builtin_amdgcn_mfma_f32_32x32x16_bf16(pa0, PKV(f.l0, f.h0), od, 0, 0, 0);
;   od = __builtin_amdgcn_mfma_f32_32x32x16_bf16(pa1, PKV(f.l1, f.h1), od, 0, 0, 0);
;   od = __builtin_amdgcn_mfma_f32_32x32x16_bf16(pa2, PKV(f.l2, f.h2), od, 0, 0, 0);
;   od = __builtin_amdgcn_mfma_f32_32x32x16_bf16(pa3, PKV(f.l3, f.h3), od, 0, 0, 0);
;     ...
; }
; __device__ __forceinline__ void pv_all(f32x16* o, int vb, bf16x8 pa0, bf16x8 pa1, bf16x8 pa2, bf16x8 pa3) {
;   VFrag fc, fn;
;   pv_reads<0>(fc, vb);
;   PV_STEP(0); PV_STEP(1); PV_STEP(2); PV_STEP(3); PV_STEP(4); PV_STEP(5); PV_STEP(6);
;   asm volatile("s_waitcnt lgkmcnt(0)" ::: "memory"); SBAR(); pv_mma(o[7], fc, pa0, pa1, pa2, pa3);
; }
	v_exp_f32_e32 v140, v140
	v_exp_f32_e32 v141, v141
	v_exp_f32_e32 v142, v142
	v_exp_f32_e32 v143, v143
	v_exp_f32_e32 v144, v144
	v_exp_f32_e32 v145, v145
	v_exp_f32_e32 v146, v146
	v_exp_f32_e32 v147, v147
	v_exp_f32_e32 v148, v148
	v_exp_f32_e32 v149, v149
	v_exp_f32_e32 v150, v150
	v_exp_f32_e32 v151, v151
	v_exp_f32_e32 v152, v152
	v_exp_f32_e32 v153, v153
	v_exp_f32_e32 v154, v154
	v_exp_f32_e32 v155, v155
	v_exp_f32_e32 v156, v156
	v_exp_f32_e32 v157, v157
	v_exp_f32_e32 v158, v158
	v_exp_f32_e32 v159, v159
	v_exp_f32_e32 v160, v160
	v_exp_f32_e32 v161, v161
	v_add_f32_e32 v194, v130, v131
	v_add_f32_e32 v194, v194, v132
	v_add_f32_e32 v194, v194, v133
	v_add_f32_e32 v194, v194, v138
	v_add_f32_e32 v194, v194, v139
	v_add_f32_e32 v194, v194, v140
	v_add_f32_e32 v194, v194, v141
	v_add_f32_e32 v194, v194, v146
	v_add_f32_e32 v194, v194, v147
	v_add_f32_e32 v194, v194, v148
	v_add_f32_e32 v194, v194, v149
	v_add_f32_e32 v194, v194, v154
	v_add_f32_e32 v194, v194, v155
	v_add_f32_e32 v194, v194, v156
	v_add_f32_e32 v194, v194, v157
	v_add_f32_e32 v195, v134, v135
	v_add_f32_e32 v195, v195, v136
	v_add_f32_e32 v195, v195, v137
	v_add_f32_e32 v195, v195, v142
	v_add_f32_e32 v195, v195, v143
	v_add_f32_e32 v195, v195, v144
	v_add_f32_e32 v195, v195, v145
	v_add_f32_e32 v195, v195, v150
	v_add_f32_e32 v195, v195, v151
	v_add_f32_e32 v195, v195, v152
	v_add_f32_e32 v195, v195, v153
	v_add_f32_e32 v195, v195, v158
	v_add_f32_e32 v195, v195, v159
	v_add_f32_e32 v195, v195, v160
	v_add_f32_e32 v195, v195, v161
	v_fma_f32 v250, v250, v236, v194
	v_fma_f32 v234, v234, v240, v195
	v_cvt_pk_bf16_f32 v130, v130, v131
	v_cvt_pk_bf16_f32 v131, v132, v133
	v_cvt_pk_bf16_f32 v132, v138, v139
	v_cvt_pk_bf16_f32 v133, v140, v141
	v_cvt_pk_bf16_f32 v134, v134, v135
	v_cvt_pk_bf16_f32 v135, v136, v137
	v_cvt_pk_bf16_f32 v136, v142, v143
	v_cvt_pk_bf16_f32 v137, v144, v145
	v_cvt_pk_bf16_f32 v138, v146, v147
	v_cvt_pk_bf16_f32 v139, v148, v149
	v_cvt_pk_bf16_f32 v140, v154, v155
	v_cvt_pk_bf16_f32 v141, v156, v157
	v_cvt_pk_bf16_f32 v142, v150, v151
	v_cvt_pk_bf16_f32 v143, v152, v153
	v_cvt_pk_bf16_f32 v144, v158, v159
	v_cvt_pk_bf16_f32 v145, v160, v161
	v_add_u32_e32 v244, s98, v248
	ds_read_b64_tr_b16 v[146:147], v244
	ds_read_b64_tr_b16 v[148:149], v244 offset:4096
	ds_read_b64_tr_b16 v[150:151], v244 offset:8192
	ds_read_b64_tr_b16 v[152:153], v244 offset:12288
	ds_read_b64_tr_b16 v[154:155], v244 offset:256
	ds_read_b64_tr_b16 v[156:157], v244 offset:4352
	ds_read_b64_tr_b16 v[158:159], v244 offset:8448
	ds_read_b64_tr_b16 v[160:161], v244 offset:12544
	ds_read_b64_tr_b16 v[194:195], v244 offset:512
	ds_read_b64_tr_b16 v[196:197], v244 offset:4608
	ds_read_b64_tr_b16 v[198:199], v244 offset:8704
	ds_read_b64_tr_b16 v[200:201], v244 offset:12800
	s_waitcnt lgkmcnt(8)
	v_mfma_f32_16x16x32_bf16 v[2:5], v[146:149], v[130:133], v[2:5]
	v_mfma_f32_16x16x32_bf16 v[6:9], v[146:149], v[134:137], v[6:9]
	v_mfma_f32_16x16x32_bf16 v[2:5], v[150:153], v[138:141], v[2:5]
	v_mfma_f32_16x16x32_bf16 v[6:9], v[150:153], v[142:145], v[6:9]
	ds_read_b64_tr_b16 v[146:147], v244 offset:768
	ds_read_b64_tr_b16 v[148:149], v244 offset:4864
	ds_read_b64_tr_b16 v[150:151], v244 offset:8960
	ds_read_b64_tr_b16 v[152:153], v244 offset:13056
	s_waitcnt lgkmcnt(8)
	v_mfma_f32_16x16x32_bf16 v[10:13], v[154:157], v[130:133], v[10:13]
	v_mfma_f32_16x16x32_bf16 v[14:17], v[154:157], v[134:137], v[14:17]
	v_mfma_f32_16x16x32_bf16 v[10:13], v[158:161], v[138:141], v[10:13]
	v_mfma_f32_16x16x32_bf16 v[14:17], v[158:161], v[142:145], v[14:17]
	ds_read_b64_tr_b16 v[154:155], v244 offset:1024
	ds_read_b64_tr_b16 v[156:157], v244 offset:5120
	ds_read_b64_tr_b16 v[158:159], v244 offset:9216
	ds_read_b64_tr_b16 v[160:161], v244 offset:13312
	s_waitcnt lgkmcnt(8)
	v_mfma_f32_16x16x32_bf16 v[114:117], v[194:197], v[130:133], v[114:117]
	v_mfma_f32_16x16x32_bf16 v[118:121], v[194:197], v[134:137], v[118:121]
	v_mfma_f32_16x16x32_bf16 v[114:117], v[198:201], v[138:141], v[114:117]
	v_mfma_f32_16x16x32_bf16 v[118:121], v[198:201], v[142:145], v[118:121]
	ds_read_b64_tr_b16 v[194:195], v244 offset:1280
	ds_read_b64_tr_b16 v[196:197], v244 offset:5376
	ds_read_b64_tr_b16 v[198:199], v244 offset:9472
	ds_read_b64_tr_b16 v[200:201], v244 offset:13568
	s_waitcnt lgkmcnt(8)
	v_mfma_f32_16x16x32_bf16 v[122:125], v[146:149], v[130:133], v[122:125]
	v_mfma_f32_16x16x32_bf16 v[126:129], v[146:149], v[134:137], v[126:129]
	v_mfma_f32_16x16x32_bf16 v[122:125], v[150:153], v[138:141], v[122:125]
	v_mfma_f32_16x16x32_bf16 v[126:129], v[150:153], v[142:145], v[126:129]
	ds_read_b64_tr_b16 v[146:147], v244 offset:1536
	ds_read_b64_tr_b16 v[148:149], v244 offset:5632
	ds_read_b64_tr_b16 v[150:151], v244 offset:9728
	ds_read_b64_tr_b16 v[152:153], v244 offset:13824
	s_waitcnt lgkmcnt(8)
	v_mfma_f32_16x16x32_bf16 v[98:101], v[154:157], v[130:133], v[98:101]
	v_mfma_f32_16x16x32_bf16 v[102:105], v[154:157], v[134:137], v[102:105]
	v_mfma_f32_16x16x32_bf16 v[98:101], v[158:161], v[138:141], v[98:101]
	v_mfma_f32_16x16x32_bf16 v[102:105], v[158:161], v[142:145], v[102:105]
	ds_read_b64_tr_b16 v[154:155], v244 offset:1792
	ds_read_b64_tr_b16 v[156:157], v244 offset:5888
	ds_read_b64_tr_b16 v[158:159], v244 offset:9984
	ds_read_b64_tr_b16 v[160:161], v244 offset:14080
	s_waitcnt lgkmcnt(8)
	v_mfma_f32_16x16x32_bf16 v[106:109], v[194:197], v[130:133], v[106:109]
	v_mfma_f32_16x16x32_bf16 v[110:113], v[194:197], v[134:137], v[110:113]
	v_mfma_f32_16x16x32_bf16 v[106:109], v[198:201], v[138:141], v[106:109]
	v_mfma_f32_16x16x32_bf16 v[110:113], v[198:201], v[142:145], v[110:113]
	ds_read_b64_tr_b16 v[194:195], v244 offset:16384
	ds_read_b64_tr_b16 v[196:197], v244 offset:20480
	ds_read_b64_tr_b16 v[198:199], v244 offset:24576
	ds_read_b64_tr_b16 v[200:201], v244 offset:28672
	s_waitcnt lgkmcnt(8)
; template <int B> __device__ __forceinline__ void pv_reads(VFrag& f, int vb) {
;   constexpr int base = (B >> 2) * 16384 + (B & 3) * 512;
;   f.l0 = tr_read<base + 0 * 4096>(vb); f.h0 = tr_read<base + 0 * 4096 + 2048>(vb); f.l1 = tr_read<base + 1 * 4096>(vb); f.h1 = tr_read<base + 1 * 4096 + 2048>(vb);
;   f.l2 = tr_read<base + 2 * 4096>(vb); f.h2 = tr_read<base + 2 * 4096 + 2048>(vb); f.l3 = tr_read<base + 3 * 4096>(vb); f.h3 = tr_read<base + 3 * 4096 + 2048>(vb);
; }
; __device__ __forceinline__ void pv_mma(f32x16& od, const VFrag& f, bf16x8 pa0, bf16x8 pa1, bf16x8 pa2, bf16x8 pa3) {
;     ...
;   od = __builtin_amdgcn_mfma_f32_32x32x16_bf16(pa0, PKV(f.l0, f.h0), od, 0, 0, 0);
;   od = __builtin_amdgcn_mfma_f32_32x32x16_bf16(pa1, PKV(f.l1, f.h1), od, 0, 0, 0);
;   od = __builtin_amdgcn_mfma_f32_32x32x16_bf16(pa2, PKV(f.l2, f.h2), od, 0, 0, 0);
;   od = __builtin_amdgcn_mfma_f32_32x32x16_bf16(pa3, PKV(f.l3, f.h3), od, 0, 0, 0);
;     ...
; }
; __device__ __forceinline__ void pv_all(f32x16* o, int vb, bf16x8 pa0, bf16x8 pa1, bf16x8 pa2, bf16x8 pa3) {
;   VFrag fc, fn;
;   pv_reads<0>(fc, vb);
;   PV_STEP(0); PV_STEP(1); PV_STEP(2); PV_STEP(3); PV_STEP(4); PV_STEP(5); PV_STEP(6);
;   asm volatile("s_waitcnt lgkmcnt(0)" ::: "memory"); SBAR(); pv_mma(o[7], fc, pa0, pa1, pa2, pa3);
; }
; __device__ __forceinline__ void attn_body256(const bf16_t* __restrict__ Qb, const bf16_t* __restrict__ Kh, const bf16_t* __restrict__ Vh,
;                                              bf16_t* Ob, int seq, unsigned char* lds, float lam, int MODE, bf16_t* Ab, const float* wsub) {
;     ...
;   const int NT = seq / KVBLK;
;   A2_DMA(0, 0); A2_DMA(1, 1);
;   float m_reg = -1e30f, l_reg = 0; f32x16 o[8] = {}; bf16x8 qr[8];
;   const bf16_t* Qw = Qb + (long)(wid * QBLK + r32) * LDQ + hi * 8;
; #pragma unroll
;   for (int d0 = 0; d0 < 8; ++d0) qr[d0] = *reinterpret_cast<const bf16x8*>(Qw + d0 * 16);
;   const int vb0 = (int)(uintptr_t)lds + v_rd_base(lane);
;   asm volatile("s_waitcnt vmcnt(0)" ::: "memory"); __syncthreads();
;   for (int j = 0; j < NT; ++j) {
;     const int b = j & 1;
;     f32x16 p0, p1; float mn, alpha; bf16x8 pa0, pa1, pa2, pa3;
;     SBAR(); qkt(p0, p1, (const bf16_t*)(lds + A2_KOFF + b * A2_KBUF), qr, r32, hi);
;     partialSM(p0, p1, m_reg, mn, alpha);
;     if (__any(alpha < 1.f)) { if (hi == 0) al_l[r32] = alpha; asm volatile("s_waitcnt lgkmcnt(0)" ::: "memory");
; #pragma unroll
	v_mfma_f32_16x16x32_bf16 v[82:85], v[146:149], v[130:133], v[82:85]
	v_mfma_f32_16x16x32_bf16 v[86:89], v[146:149], v[134:137], v[86:89]
	v_mfma_f32_16x16x32_bf16 v[82:85], v[150:153], v[138:141], v[82:85]
	v_mfma_f32_16x16x32_bf16 v[86:89], v[150:153], v[142:145], v[86:89]
	ds_read_b64_tr_b16 v[146:147], v244 offset:16640
	ds_read_b64_tr_b16 v[148:149], v244 offset:20736
	ds_read_b64_tr_b16 v[150:151], v244 offset:24832
	ds_read_b64_tr_b16 v[152:153], v244 offset:28928
	s_waitcnt lgkmcnt(8)
	v_mfma_f32_16x16x32_bf16 v[90:93], v[154:157], v[130:133], v[90:93]
	v_mfma_f32_16x16x32_bf16 v[94:97], v[154:157], v[134:137], v[94:97]
	v_mfma_f32_16x16x32_bf16 v[90:93], v[158:161], v[138:141], v[90:93]
	v_mfma_f32_16x16x32_bf16 v[94:97], v[158:161], v[142:145], v[94:97]
	ds_read_b64_tr_b16 v[154:155], v244 offset:16896
	ds_read_b64_tr_b16 v[156:157], v244 offset:20992
	ds_read_b64_tr_b16 v[158:159], v244 offset:25088
	ds_read_b64_tr_b16 v[160:161], v244 offset:29184
	s_waitcnt lgkmcnt(8)
	v_mfma_f32_16x16x32_bf16 v[66:69], v[194:197], v[130:133], v[66:69]
	v_mfma_f32_16x16x32_bf16 v[70:73], v[194:197], v[134:137], v[70:73]
	v_mfma_f32_16x16x32_bf16 v[66:69], v[198:201], v[138:141], v[66:69]
	v_mfma_f32_16x16x32_bf16 v[70:73], v[198:201], v[142:145], v[70:73]
	ds_read_b64_tr_b16 v[194:195], v244 offset:17152
	ds_read_b64_tr_b16 v[196:197], v244 offset:21248
	ds_read_b64_tr_b16 v[198:199], v244 offset:25344
	ds_read_b64_tr_b16 v[200:201], v244 offset:29440
	s_waitcnt lgkmcnt(8)
	v_mfma_f32_16x16x32_bf16 v[74:77], v[146:149], v[130:133], v[74:77]
	v_mfma_f32_16x16x32_bf16 v[78:81], v[146:149], v[134:137], v[78:81]
	v_mfma_f32_16x16x32_bf16 v[74:77], v[150:153], v[138:141], v[74:77]
	v_mfma_f32_16x16x32_bf16 v[78:81], v[150:153], v[142:145], v[78:81]
	ds_read_b64_tr_b16 v[146:147], v244 offset:17408
	ds_read_b64_tr_b16 v[148:149], v244 offset:21504
	ds_read_b64_tr_b16 v[150:151], v244 offset:25600
	ds_read_b64_tr_b16 v[152:153], v244 offset:29696
	s_waitcnt lgkmcnt(8)
	v_mfma_f32_16x16x32_bf16 v[50:53], v[154:157], v[130:133], v[50:53]
	v_mfma_f32_16x16x32_bf16 v[54:57], v[154:157], v[134:137], v[54:57]
	v_mfma_f32_16x16x32_bf16 v[50:53], v[158:161], v[138:141], v[50:53]
	v_mfma_f32_16x16x32_bf16 v[54:57], v[158:161], v[142:145], v[54:57]
	ds_read_b64_tr_b16 v[154:155], v244 offset:17664
	ds_read_b64_tr_b16 v[156:157], v244 offset:21760
	ds_read_b64_tr_b16 v[158:159], v244 offset:25856
	ds_read_b64_tr_b16 v[160:161], v244 offset:29952
	s_waitcnt lgkmcnt(8)
	v_mfma_f32_16x16x32_bf16 v[58:61], v[194:197], v[130:133], v[58:61]
	v_mfma_f32_16x16x32_bf16 v[62:65], v[194:197], v[134:137], v[62:65]
	v_mfma_f32_16x16x32_bf16 v[58:61], v[198:201], v[138:141], v[58:61]
	v_mfma_f32_16x16x32_bf16 v[62:65], v[198:201], v[142:145], v[62:65]
	ds_read_b64_tr_b16 v[194:195], v244 offset:17920
	ds_read_b64_tr_b16 v[196:197], v244 offset:22016
	ds_read_b64_tr_b16 v[198:199], v244 offset:26112
	ds_read_b64_tr_b16 v[200:201], v244 offset:30208
	s_waitcnt lgkmcnt(8)
	v_mfma_f32_16x16x32_bf16 v[34:37], v[146:149], v[130:133], v[34:37]
	v_mfma_f32_16x16x32_bf16 v[38:41], v[146:149], v[134:137], v[38:41]
	v_mfma_f32_16x16x32_bf16 v[34:37], v[150:153], v[138:141], v[34:37]
	v_mfma_f32_16x16x32_bf16 v[38:41], v[150:153], v[142:145], v[38:41]
	ds_read_b64_tr_b16 v[146:147], v244 offset:18176
	ds_read_b64_tr_b16 v[148:149], v244 offset:22272
	ds_read_b64_tr_b16 v[150:151], v244 offset:26368
	ds_read_b64_tr_b16 v[152:153], v244 offset:30464
	s_waitcnt lgkmcnt(8)
	v_mfma_f32_16x16x32_bf16 v[42:45], v[154:157], v[130:133], v[42:45]
	v_mfma_f32_16x16x32_bf16 v[46:49], v[154:157], v[134:137], v[46:49]
	v_mfma_f32_16x16x32_bf16 v[42:45], v[158:161], v[138:141], v[42:45]
	v_mfma_f32_16x16x32_bf16 v[46:49], v[158:161], v[142:145], v[46:49]
	s_waitcnt lgkmcnt(4)
	v_mfma_f32_16x16x32_bf16 v[18:21], v[194:197], v[130:133], v[18:21]
	v_mfma_f32_16x16x32_bf16 v[22:25], v[194:197], v[134:137], v[22:25]
	v_mfma_f32_16x16x32_bf16 v[18:21], v[198:201], v[138:141], v[18:21]
	v_mfma_f32_16x16x32_bf16 v[22:25], v[198:201], v[142:145], v[22:25]
	s_waitcnt lgkmcnt(0)
	v_mfma_f32_16x16x32_bf16 v[26:29], v[146:149], v[130:133], v[26:29]
	v_mfma_f32_16x16x32_bf16 v[30:33], v[146:149], v[134:137], v[30:33]
	v_mfma_f32_16x16x32_bf16 v[26:29], v[150:153], v[138:141], v[26:29]
	v_mfma_f32_16x16x32_bf16 v[30:33], v[150:153], v[142:145], v[30:33]
	s_waitcnt vmcnt(0)
	s_barrier
	s_xor_b32 s9, s25, 1
	s_lshl_b32 s9, s9, 14
	s_add_i32 s9, s9, 0x10000
	v_add_u32_e32 v230, s9, v232
	v_add_u32_e32 v247, s9, v233
	v_add_u32_e32 v239, s9, v242
	v_add_u32_e32 v245, s9, v243
	ds_read_b128 v[194:197], v230
	ds_read_b128 v[198:201], v230 offset:4096
	ds_read_b128 v[202:205], v230 offset:8192
	ds_read_b128 v[206:209], v230 offset:12288
	ds_read_b128 v[210:213], v247
	ds_read_b128 v[214:217], v247 offset:4096
	s_cmp_ge_u32 s13, s19
	s_cbranch_scc1 .Lat_x_nodma
	s_add_i32 s9, s22, s24
	s_add_i32 s8, s21, s100
	v_lshl_add_u64 v[130:131], v[220:221], 0, s[14:15]
	s_mov_b32 m0, s9
	v_lshl_add_u64 v[132:133], v[222:223], 0, s[14:15]
	global_load_lds_dwordx4 v[130:131], off
	s_add_i32 m0, s9, 0x2000
	v_lshl_add_u64 v[134:135], v[224:225], 0, s[14:15]
	global_load_lds_dwordx4 v[132:133], off
	v_lshl_add_u64 v[138:139], v[134:135], 0, s[54:55]
	s_mov_b32 m0, s8
	v_lshl_add_u64 v[134:135], v[134:135], 0, s[4:5]
	global_load_lds_dwordx4 v[138:139], off
	s_add_i32 m0, s8, 0x4000
	v_lshl_add_u64 v[136:137], v[226:227], 0, s[14:15]
	global_load_lds_dwordx4 v[134:135], off
	v_lshl_add_u64 v[140:141], v[136:137], 0, s[54:55]
	s_add_i32 m0, s8, 0x2000
	v_lshl_add_u64 v[136:137], v[136:137], 0, s[4:5]
	global_load_lds_dwordx4 v[140:141], off
	s_add_i32 m0, s8, 0x6000
	s_nop 0
	global_load_lds_dwordx4 v[136:137], off

; #define SBAR() __builtin_amdgcn_sched_barrier(0)
; #define PV_STEP(B) do { pv_reads<(B) + 1>(fn, vb); asm volatile("s_waitcnt lgkmcnt(8)" ::: "memory"); SBAR(); pv_mma(o[B], fc, pa0, pa1, pa2, pa3); SBAR(); fc = fn; } while (0)
; template <int B> __device__ __forceinline__ void pv_reads(VFrag& f, int vb) {
;   constexpr int base = (B >> 2) * 16384 + (B & 3) * 512;
;   f.l0 = tr_read<base + 0 * 4096>(vb); f.h0 = tr_read<base + 0 * 4096 + 2048>(vb); f.l1 = tr_read<base + 1 * 4096>(vb); f.h1 = tr_read<base + 1 * 4096 + 2048>(vb);
;   f.l2 = tr_read<base + 2 * 4096>(vb); f.h2 = tr_read<base + 2 * 4096 + 2048>(vb); f.l3 = tr_read<base + 3 * 4096>(vb); f.h3 = tr_read<base + 3 * 4096 + 2048>(vb);
; }
; __device__ __forceinline__ void pv_mma(f32x16& od, const VFrag& f, bf16x8 pa0, bf16x8 pa1, bf16x8 pa2, bf16x8 pa3) {
;     ...
;   od = __builtin_amdgcn_mfma_f32_32x32x16_bf16(pa0, PKV(f.l0, f.h0), od, 0, 0, 0);
;   od = __builtin_amdgcn_mfma_f32_32x32x16_bf16(pa1, PKV(f.l1, f.h1), od, 0, 0, 0);
;   od = __builtin_amdgcn_mfma_f32_32x32x16_bf16(pa2, PKV(f.l2, f.h2), od, 0, 0, 0);
;   od = __builtin_amdgcn_mfma_f32_32x32x16_bf16(pa3, PKV(f.l3, f.h3), od, 0, 0, 0);
;     ...
; }
; __device__ __forceinline__ void pv_all(f32x16* o, int vb, bf16x8 pa0, bf16x8 pa1, bf16x8 pa2, bf16x8 pa3) {
;   VFrag fc, fn;
;   pv_reads<0>(fc, vb);
;   PV_STEP(0); PV_STEP(1); PV_STEP(2); PV_STEP(3); PV_STEP(4); PV_STEP(5); PV_STEP(6);
;   asm volatile("s_waitcnt lgkmcnt(0)" ::: "memory"); SBAR(); pv_mma(o[7], fc, pa0, pa1, pa2, pa3);
; }
.Lat_y_top:
	s_waitcnt lgkmcnt(8)
	v_mfma_f32_16x16x32_bf16 v[2:5], v[146:149], v[130:133], v[2:5]
	v_mfma_f32_16x16x32_bf16 v[6:9], v[146:149], v[134:137], v[6:9]
	v_mfma_f32_16x16x32_bf16 v[2:5], v[150:153], v[138:141], v[2:5]
	v_mfma_f32_16x16x32_bf16 v[6:9], v[150:153], v[142:145], v[6:9]
	ds_read_b64_tr_b16 v[146:147], v244 offset:768
	ds_read_b64_tr_b16 v[148:149], v244 offset:4864
	ds_read_b64_tr_b16 v[150:151], v244 offset:8960
	ds_read_b64_tr_b16 v[152:153], v244 offset:13056
	s_waitcnt lgkmcnt(8)
	v_mfma_f32_16x16x32_bf16 v[10:13], v[154:157], v[130:133], v[10:13]
	v_mfma_f32_16x16x32_bf16 v[14:17], v[154:157], v[134:137], v[14:17]
	v_mfma_f32_16x16x32_bf16 v[10:13], v[158:161], v[138:141], v[10:13]
	v_mfma_f32_16x16x32_bf16 v[14:17], v[158:161], v[142:145], v[14:17]
	ds_read_b64_tr_b16 v[154:155], v244 offset:1024
	ds_read_b64_tr_b16 v[156:157], v244 offset:5120
	ds_read_b64_tr_b16 v[158:159], v244 offset:9216
	ds_read_b64_tr_b16 v[160:161], v244 offset:13312
	s_waitcnt lgkmcnt(8)
	v_mfma_f32_16x16x32_bf16 v[114:117], v[194:197], v[130:133], v[114:117]
	v_mfma_f32_16x16x32_bf16 v[118:121], v[194:197], v[134:137], v[118:121]
	v_mfma_f32_16x16x32_bf16 v[114:117], v[198:201], v[138:141], v[114:117]
	v_mfma_f32_16x16x32_bf16 v[118:121], v[198:201], v[142:145], v[118:121]
	ds_read_b64_tr_b16 v[194:195], v244 offset:1280
	ds_read_b64_tr_b16 v[196:197], v244 offset:5376
	ds_read_b64_tr_b16 v[198:199], v244 offset:9472
	ds_read_b64_tr_b16 v[200:201], v244 offset:13568
	s_waitcnt lgkmcnt(8)
	v_mfma_f32_16x16x32_bf16 v[122:125], v[146:149], v[130:133], v[122:125]
	v_mfma_f32_16x16x32_bf16 v[126:129], v[146:149], v[134:137], v[126:129]
	v_mfma_f32_16x16x32_bf16 v[122:125], v[150:153], v[138:141], v[122:125]
	v_mfma_f32_16x16x32_bf16 v[126:129], v[150:153], v[142:145], v[126:129]
	ds_read_b64_tr_b16 v[146:147], v244 offset:1536
	ds_read_b64_tr_b16 v[148:149], v244 offset:5632
	ds_read_b64_tr_b16 v[150:151], v244 offset:9728
	ds_read_b64_tr_b16 v[152:153], v244 offset:13824
	s_waitcnt lgkmcnt(8)
	v_mfma_f32_16x16x32_bf16 v[98:101], v[154:157], v[130:133], v[98:101]
	v_mfma_f32_16x16x32_bf16 v[102:105], v[154:157], v[134:137], v[102:105]
	v_mfma_f32_16x16x32_bf16 v[98:101], v[158:161], v[138:141], v[98:101]
	v_mfma_f32_16x16x32_bf16 v[102:105], v[158:161], v[142:145], v[102:105]
	ds_read_b64_tr_b16 v[154:155], v244 offset:1792
	ds_read_b64_tr_b16 v[156:157], v244 offset:5888
	ds_read_b64_tr_b16 v[158:159], v244 offset:9984
	ds_read_b64_tr_b16 v[160:161], v244 offset:14080
	s_waitcnt lgkmcnt(8)
	v_mfma_f32_16x16x32_bf16 v[106:109], v[194:197], v[130:133], v[106:109]
	v_mfma_f32_16x16x32_bf16 v[110:113], v[194:197], v[134:137], v[110:113]
	v_mfma_f32_16x16x32_bf16 v[106:109], v[198:201], v[138:141], v[106:109]
	v_mfma_f32_16x16x32_bf16 v[110:113], v[198:201], v[142:145], v[110:113]
	ds_read_b64_tr_b16 v[194:195], v244 offset:16384
	ds_read_b64_tr_b16 v[196:197], v244 offset:20480
	ds_read_b64_tr_b16 v[198:199], v244 offset:24576
	ds_read_b64_tr_b16 v[200:201], v244 offset:28672
	s_waitcnt lgkmcnt(8)
	v_mfma_f32_16x16x32_bf16 v[82:85], v[146:149], v[130:133], v[82:85]
	v_mfma_f32_16x16x32_bf16 v[86:89], v[146:149], v[134:137], v[86:89]
	v_mfma_f32_16x16x32_bf16 v[82:85], v[150:153], v[138:141], v[82:85]
	v_mfma_f32_16x16x32_bf16 v[86:89], v[150:153], v[142:145], v[86:89]
	ds_read_b64_tr_b16 v[146:147], v244 offset:16640
	ds_read_b64_tr_b16 v[148:149], v244 offset:20736
	ds_read_b64_tr_b16 v[150:151], v244 offset:24832
	ds_read_b64_tr_b16 v[152:153], v244 offset:28928
	s_waitcnt lgkmcnt(8)
	v_mfma_f32_16x16x32_bf16 v[90:93], v[154:157], v[130:133], v[90:93]
	v_mfma_f32_16x16x32_bf16 v[94:97], v[154:157], v[134:137], v[94:97]
	v_mfma_f32_16x16x32_bf16 v[90:93], v[158:161], v[138:141], v[90:93]
	v_mfma_f32_16x16x32_bf16 v[94:97], v[158:161], v[142:145], v[94:97]
	ds_read_b64_tr_b16 v[154:155], v244 offset:16896
	ds_read_b64_tr_b16 v[156:157], v244 offset:20992
	ds_read_b64_tr_b16 v[158:159], v244 offset:25088
	ds_read_b64_tr_b16 v[160:161], v244 offset:29184
	s_waitcnt lgkmcnt(8)
	v_mfma_f32_16x16x32_bf16 v[66:69], v[194:197], v[130:133], v[66:69]
	v_mfma_f32_16x16x32_bf16 v[70:73], v[194:197], v[134:137], v[70:73]
	v_mfma_f32_16x16x32_bf16 v[66:69], v[198:201], v[138:141], v[66:69]
	v_mfma_f32_16x16x32_bf16 v[70:73], v[198:201], v[142:145], v[70:73]
	ds_read_b64_tr_b16 v[194:195], v244 offset:17152
	ds_read_b64_tr_b16 v[196:197], v244 offset:21248
	ds_read_b64_tr_b16 v[198:199], v244 offset:25344
	ds_read_b64_tr_b16 v[200:201], v244 offset:29440
	s_waitcnt lgkmcnt(8)
	v_mfma_f32_16x16x32_bf16 v[74:77], v[146:149], v[130:133], v[74:77]
	v_mfma_f32_16x16x32_bf16 v[78:81], v[146:149], v[134:137], v[78:81]
	v_mfma_f32_16x16x32_bf16 v[74:77], v[150:153], v[138:141], v[74:77]
	v_mfma_f32_16x16x32_bf16 v[78:81], v[150:153], v[142:145], v[78:81]
	ds_read_b64_tr_b16 v[146:147], v244 offset:17408
	ds_read_b64_tr_b16 v[148:149], v244 offset:21504
	ds_read_b64_tr_b16 v[150:151], v244 offset:25600
	ds_read_b64_tr_b16 v[152:153], v244 offset:29696
	s_waitcnt lgkmcnt(8)
	v_mfma_f32_16x16x32_bf16 v[50:53], v[154:157], v[130:133], v[50:53]
	v_mfma_f32_16x16x32_bf16 v[54:57], v[154:157], v[134:137], v[54:57]
	v_mfma_f32_16x16x32_bf16 v[50:53], v[158:161], v[138:141], v[50:53]
	v_mfma_f32_16x16x32_bf16 v[54:57], v[158:161], v[142:145], v[54:57]
	ds_read_b64_tr_b16 v[154:155], v244 offset:17664
	ds_read_b64_tr_b16 v[156:157], v244 offset:21760
	ds_read_b64_tr_b16 v[158:159], v244 offset:25856
	ds_read_b64_tr_b16 v[160:161], v244 offset:29952
	s_waitcnt lgkmcnt(8)
; #define SBAR() __builtin_amdgcn_sched_barrier(0)
; __device__ __forceinline__ int crow(int r, int hi) { return (r & 3) + 8 * (r >> 2) + 4 * hi; }
; __device__ __forceinline__ int v_rd_base(int lane) { return ((lane & 3) << 3) | (((lane >> 2) & 3) << 6) | (((lane >> 4) & 1) << 5) | (((lane >> 5) & 1) << 8); }
; __device__ __forceinline__ void qkt(f32x16& p0, f32x16& p1, const bf16_t* Ks, const bf16x8* qr, int r32, int hi) {
;   p0 = f32x16{}; p1 = f32x16{};
;   for (int d0 = 0; d0 < 8; ++d0) { int cb = (d0 * 16 + hi * 8) * 2;
;     bf16x8 b0 = *reinterpret_cast<const bf16x8*>((const char*)Ks + KSWZ(r32, cb));
;     bf16x8 b1 = *reinterpret_cast<const bf16x8*>((const char*)Ks + KSWZ(32 + r32, cb));
;     p0 = __builtin_amdgcn_mfma_f32_32x32x16_bf16(b0, qr[d0], p0, 0, 0, 0);
;     p1 = __builtin_amdgcn_mfma_f32_32x32x16_bf16(b1, qr[d0], p1, 0, 0, 0); }
; __device__ __forceinline__ void attn_body256(const bf16_t* __restrict__ Qb, const bf16_t* __restrict__ Kh, const bf16_t* __restrict__ Vh,
;                                              bf16_t* Ob, int seq, unsigned char* lds, float lam, int MODE, bf16_t* Ab, const float* wsub) {
;     ...
;   const int NT = seq / KVBLK;
;   A2_DMA(0, 0); A2_DMA(1, 1);
;   float m_reg = -1e30f, l_reg = 0; f32x16 o[8] = {}; bf16x8 qr[8];
;   const bf16_t* Qw = Qb + (long)(wid * QBLK + r32) * LDQ + hi * 8;
; #pragma unroll
;   for (int d0 = 0; d0 < 8; ++d0) qr[d0] = *reinterpret_cast<const bf16x8*>(Qw + d0 * 16);
;   const int vb0 = (int)(uintptr_t)lds + v_rd_base(lane);
;   asm volatile("s_waitcnt vmcnt(0)" ::: "memory"); __syncthreads();
;   for (int j = 0; j < NT; ++j) {
;     const int b = j & 1;
;     f32x16 p0, p1; float mn, alpha; bf16x8 pa0, pa1, pa2, pa3;
;     SBAR(); qkt(p0, p1, (const bf16_t*)(lds + A2_KOFF + b * A2_KBUF), qr, r32, hi);
;     partialSM(p0, p1, m_reg, mn, alpha);
;     if (__any(alpha < 1.f)) { if (hi == 0) al_l[r32] = alpha; asm volatile("s_waitcnt lgkmcnt(0)" ::: "memory");
; #pragma unroll
;       for (int r = 0; r < 16; ++r) { const float a = al_l[crow(r, hi)];
; #pragma unroll
;         for (int d = 0; d < 8; ++d) o[d][r] *= a; } }
;     finishSM(p0, p1, alpha, l_reg, pa0, pa1, pa2, pa3); SBAR();
;     pv_all(o, vb0 + b * A2_VBUF, pa0, pa1, pa2, pa3);
;     asm volatile("s_waitcnt vmcnt(0)" ::: "memory"); __syncthreads();
;     if (j + 2 < NT) A2_DMA(j + 2, b);
	v_mfma_f32_16x16x32_bf16 v[58:61], v[194:197], v[130:133], v[58:61]
	v_mfma_f32_16x16x32_bf16 v[62:65], v[194:197], v[134:137], v[62:65]
	v_mfma_f32_16x16x32_bf16 v[58:61], v[198:201], v[138:141], v[58:61]
	v_mfma_f32_16x16x32_bf16 v[62:65], v[198:201], v[142:145], v[62:65]
	ds_read_b64_tr_b16 v[194:195], v244 offset:17920
	ds_read_b64_tr_b16 v[196:197], v244 offset:22016
	ds_read_b64_tr_b16 v[198:199], v244 offset:26112
	ds_read_b64_tr_b16 v[200:201], v244 offset:30208
	s_waitcnt lgkmcnt(8)
	v_mfma_f32_16x16x32_bf16 v[34:37], v[146:149], v[130:133], v[34:37]
	v_mfma_f32_16x16x32_bf16 v[38:41], v[146:149], v[134:137], v[38:41]
	v_mfma_f32_16x16x32_bf16 v[34:37], v[150:153], v[138:141], v[34:37]
	v_mfma_f32_16x16x32_bf16 v[38:41], v[150:153], v[142:145], v[38:41]
	ds_read_b64_tr_b16 v[146:147], v244 offset:18176
	ds_read_b64_tr_b16 v[148:149], v244 offset:22272
	ds_read_b64_tr_b16 v[150:151], v244 offset:26368
	ds_read_b64_tr_b16 v[152:153], v244 offset:30464
	s_waitcnt lgkmcnt(8)
	v_mfma_f32_16x16x32_bf16 v[42:45], v[154:157], v[130:133], v[42:45]
	v_mfma_f32_16x16x32_bf16 v[46:49], v[154:157], v[134:137], v[46:49]
	v_mfma_f32_16x16x32_bf16 v[42:45], v[158:161], v[138:141], v[42:45]
	v_mfma_f32_16x16x32_bf16 v[46:49], v[158:161], v[142:145], v[46:49]
	s_waitcnt lgkmcnt(4)
	v_mfma_f32_16x16x32_bf16 v[18:21], v[194:197], v[130:133], v[18:21]
	v_mfma_f32_16x16x32_bf16 v[22:25], v[194:197], v[134:137], v[22:25]
	v_mfma_f32_16x16x32_bf16 v[18:21], v[198:201], v[138:141], v[18:21]
	v_mfma_f32_16x16x32_bf16 v[22:25], v[198:201], v[142:145], v[22:25]
	s_waitcnt lgkmcnt(0)
	v_mfma_f32_16x16x32_bf16 v[26:29], v[146:149], v[130:133], v[26:29]
	v_mfma_f32_16x16x32_bf16 v[30:33], v[146:149], v[134:137], v[30:33]
	v_mfma_f32_16x16x32_bf16 v[26:29], v[150:153], v[138:141], v[26:29]
	v_mfma_f32_16x16x32_bf16 v[30:33], v[150:153], v[142:145], v[30:33]
	s_cmp_gt_u32 s13, s19
	s_cbranch_scc1 .Lat_y_nodma
	s_sub_u32 s16, s14, 0x40000
	s_subb_u32 s17, s15, 0
	s_add_i32 s9, s22, s24
	s_add_i32 s8, s21, s99
	v_lshl_add_u64 v[130:131], v[220:221], 0, s[16:17]
	s_mov_b32 m0, s9
	v_lshl_add_u64 v[132:133], v[222:223], 0, s[16:17]
	global_load_lds_dwordx4 v[130:131], off
	s_add_i32 m0, s9, 0x2000
	v_lshl_add_u64 v[134:135], v[224:225], 0, s[16:17]
	global_load_lds_dwordx4 v[132:133], off
	v_lshl_add_u64 v[138:139], v[134:135], 0, s[54:55]
	s_mov_b32 m0, s8
	v_lshl_add_u64 v[134:135], v[134:135], 0, s[4:5]
	global_load_lds_dwordx4 v[138:139], off
	s_add_i32 m0, s8, 0x4000
	v_lshl_add_u64 v[136:137], v[226:227], 0, s[16:17]
	global_load_lds_dwordx4 v[134:135], off
	v_lshl_add_u64 v[140:141], v[136:137], 0, s[54:55]
	s_add_i32 m0, s8, 0x2000
	v_lshl_add_u64 v[136:137], v[136:137], 0, s[4:5]
	global_load_lds_dwordx4 v[140:141], off
	s_add_i32 m0, s8, 0x6000
	s_nop 0
	global_load_lds_dwordx4 v[136:137], off
.Lat_y_nodma:
.Lat_y_qk:
	s_add_i32 s8, s13, -2
	s_and_b32 s25, s8, 1
	s_lshl_b32 s24, s25, 14
	s_add_i32 s8, s24, 0x10000
	v_add_u32_e32 v230, s8, v232
	v_add_u32_e32 v247, s8, v233
	v_add_u32_e32 v239, s8, v242
	v_add_u32_e32 v245, s8, v243
	s_setprio 1
	ds_read_b128 v[194:197], v230
	ds_read_b128 v[198:201], v230 offset:4096
	ds_read_b128 v[202:205], v230 offset:8192
	ds_read_b128 v[206:209], v230 offset:12288
	ds_read_b128 v[210:213], v247
	ds_read_b128 v[214:217], v247 offset:4096
	s_waitcnt lgkmcnt(4)
	v_mfma_f32_16x16x32_bf16 v[130:133], v[194:197], v[162:165], 0
	v_mfma_f32_16x16x32_bf16 v[134:137], v[194:197], v[178:181], 0
	v_mfma_f32_16x16x32_bf16 v[138:141], v[198:201], v[162:165], 0
	v_mfma_f32_16x16x32_bf16 v[142:145], v[198:201], v[178:181], 0
	ds_read_b128 v[194:197], v247 offset:8192
	ds_read_b128 v[198:201], v247 offset:12288
	s_waitcnt lgkmcnt(4)
	v_mfma_f32_16x16x32_bf16 v[146:149], v[202:205], v[162:165], 0
	v_mfma_f32_16x16x32_bf16 v[150:153], v[202:205], v[178:181], 0
	v_mfma_f32_16x16x32_bf16 v[154:157], v[206:209], v[162:165], 0
	v_mfma_f32_16x16x32_bf16 v[158:161], v[206:209], v[178:181], 0
	ds_read_b128 v[202:205], v239
	ds_read_b128 v[206:209], v239 offset:4096
	s_waitcnt lgkmcnt(4)
	v_mfma_f32_16x16x32_bf16 v[130:133], v[210:213], v[166:169], v[130:133]
	v_mfma_f32_16x16x32_bf16 v[134:137], v[210:213], v[182:185], v[134:137]
	v_mfma_f32_16x16x32_bf16 v[138:141], v[214:217], v[166:169], v[138:141]
	v_mfma_f32_16x16x32_bf16 v[142:145], v[214:217], v[182:185], v[142:145]
	ds_read_b128 v[210:213], v239 offset:8192
	ds_read_b128 v[214:217], v239 offset:12288
	s_waitcnt lgkmcnt(4)
	v_mfma_f32_16x16x32_bf16 v[146:149], v[194:197], v[166:169], v[146:149]
	v_mfma_f32_16x16x32_bf16 v[150:153], v[194:197], v[182:185], v[150:153]
	v_mfma_f32_16x16x32_bf16 v[154:157], v[198:201], v[166:169], v[154:157]
	v_mfma_f32_16x16x32_bf16 v[158:161], v[198:201], v[182:185], v[158:161]
	ds_read_b128 v[194:197], v245
	ds_read_b128 v[198:201], v245 offset:4096
	s_waitcnt lgkmcnt(4)
	v_mfma_f32_16x16x32_bf16 v[130:133], v[202:205], v[170:173], v[130:133]
	v_mfma_f32_16x16x32_bf16 v[134:137], v[202:205], v[186:189], v[134:137]
	v_mfma_f32_16x16x32_bf16 v[138:141], v[206:209], v[170:173], v[138:141]
	v_mfma_f32_16x16x32_bf16 v[142:145], v[206:209], v[186:189], v[142:145]
	ds_read_b128 v[202:205], v245 offset:8192
	ds_read_b128 v[206:209], v245 offset:12288
	s_waitcnt lgkmcnt(4)
	v_mfma_f32_16x16x32_bf16 v[146:149], v[210:213], v[170:173], v[146:149]
	v_mfma_f32_16x16x32_bf16 v[150:153], v[210:213], v[186:189], v[150:153]
	v_mfma_f32_16x16x32_bf16 v[154:157], v[214:217], v[170:173], v[154:157]
	v_mfma_f32_16x16x32_bf16 v[158:161], v[214:217], v[186:189], v[158:161]
	s_waitcnt lgkmcnt(2)
; __device__ __forceinline__ int crow(int r, int hi) { return (r & 3) + 8 * (r >> 2) + 4 * hi; }
; __device__ __forceinline__ int crow(int r, int hi) { return (r & 3) + 8 * (r >> 2) + 4 * hi; }
; __device__ __forceinline__ void partialSM(f32x16& p0, f32x16& p1, float& m_reg, float& mn, float& alpha) {
;   constexpr float C = SCALE * 1.4426950408889634f;
;   float pmax = p0[0]; for (int r = 1; r < 16; ++r) pmax = fmaxf(pmax, p0[r]); for (int r = 0; r < 16; ++r) pmax = fmaxf(pmax, p1[r]);
;   { auto rr = __builtin_amdgcn_permlane32_swap(__float_as_uint(pmax), __float_as_uint(pmax), false, false);
;     pmax = fmaxf(__uint_as_float(rr[0]), __uint_as_float(rr[1])); }
;   if (__builtin_expect(__all(pmax - m_reg <= THR / SCALE), 1)) { mn = m_reg; alpha = 1.f; }
;   else { mn = fmaxf(m_reg, pmax); alpha = __builtin_amdgcn_exp2f((m_reg - mn) * C); m_reg = mn; }
; __device__ __forceinline__ void attn_body256(const bf16_t* __restrict__ Qb, const bf16_t* __restrict__ Kh, const bf16_t* __restrict__ Vh,
;                                              bf16_t* Ob, int seq, unsigned char* lds, float lam, int MODE, bf16_t* Ab, const float* wsub) {
;     ...
;     if (__any(alpha < 1.f)) { if (hi == 0) al_l[r32] = alpha; asm volatile("s_waitcnt lgkmcnt(0)" ::: "memory");
; #pragma unroll
;       for (int r = 0; r < 16; ++r) { const float a = al_l[crow(r, hi)];
; #pragma unroll
;         for (int d = 0; d < 8; ++d) o[d][r] *= a; } }
	v_mfma_f32_16x16x32_bf16 v[130:133], v[194:197], v[174:177], v[130:133]
	v_mfma_f32_16x16x32_bf16 v[134:137], v[194:197], v[190:193], v[134:137]
	v_mfma_f32_16x16x32_bf16 v[138:141], v[198:201], v[174:177], v[138:141]
	v_mfma_f32_16x16x32_bf16 v[142:145], v[198:201], v[190:193], v[142:145]
	s_waitcnt lgkmcnt(0)
	v_mfma_f32_16x16x32_bf16 v[146:149], v[202:205], v[174:177], v[146:149]
	v_mfma_f32_16x16x32_bf16 v[150:153], v[202:205], v[190:193], v[150:153]
	v_mfma_f32_16x16x32_bf16 v[154:157], v[206:209], v[174:177], v[154:157]
	v_mfma_f32_16x16x32_bf16 v[158:161], v[206:209], v[190:193], v[158:161]
	s_setprio 0
	s_nop 6
	v_max3_f32 v194, v130, v131, v132
	v_max3_f32 v194, v194, v133, v138
	v_max3_f32 v194, v194, v139, v140
	v_max3_f32 v194, v194, v141, v146
	v_max3_f32 v194, v194, v147, v148
	v_max3_f32 v194, v194, v149, v154
	v_max3_f32 v194, v194, v155, v156
	v_max_f32_e32 v194, v194, v157
	v_max3_f32 v195, v134, v135, v136
	v_max3_f32 v195, v195, v137, v142
	v_max3_f32 v195, v195, v143, v144
	v_max3_f32 v195, v195, v145, v150
	v_max3_f32 v195, v195, v151, v152
	v_max3_f32 v195, v195, v153, v158
	v_max3_f32 v195, v195, v159, v160
	v_max_f32_e32 v195, v195, v161
	v_mov_b32_e32 v196, v194
	v_mov_b32_e32 v197, v195
	s_nop 1
	v_permlane32_swap_b32_e32 v194, v196
	v_permlane32_swap_b32_e32 v195, v197
	v_max_f32_e32 v194, v194, v196
	v_max_f32_e32 v195, v195, v197
	v_mov_b32_e32 v196, v194
	v_mov_b32_e32 v197, v195
	s_nop 1
	v_permlane16_swap_b32_e32 v194, v196
	v_permlane16_swap_b32_e32 v195, v197
	v_max_f32_e32 v194, v194, v196
	v_max_f32_e32 v195, v195, v197
	v_sub_f32_e32 v196, v194, v249
	v_sub_f32_e32 v197, v195, v246
	v_max_f32_e32 v196, v196, v197
	v_cmp_ge_f32_e32 vcc, 0x42b504f3, v196
	v_max_f32_e32 v198, v249, v194
	v_max_f32_e32 v199, v246, v195
	v_sub_f32_e32 v196, v249, v198
	v_sub_f32_e32 v197, v246, v199
	v_mul_f32_e32 v196, 0x3e0293ee, v196
	v_mul_f32_e32 v197, 0x3e0293ee, v197
	v_exp_f32_e32 v196, v196
	v_exp_f32_e32 v197, v197
	s_cmp_eq_u64 vcc, exec
	s_cselect_b64 s[8:9], -1, 0
	v_cndmask_b32_e64 v236, v196, 1.0, s[8:9]
	v_cndmask_b32_e64 v240, v197, 1.0, s[8:9]
	v_cndmask_b32_e64 v249, v198, v249, s[8:9]
	v_cndmask_b32_e64 v246, v199, v246, s[8:9]
	s_cbranch_scc1 .Lat_y_noresc
	v_pk_mul_f32 v[2:3], v[2:3], v[236:237] op_sel_hi:[1,0]
	v_pk_mul_f32 v[4:5], v[4:5], v[236:237] op_sel_hi:[1,0]
	v_pk_mul_f32 v[6:7], v[6:7], v[240:241] op_sel_hi:[1,0]
	v_pk_mul_f32 v[8:9], v[8:9], v[240:241] op_sel_hi:[1,0]
	v_pk_mul_f32 v[10:11], v[10:11], v[236:237] op_sel_hi:[1,0]
	v_pk_mul_f32 v[12:13], v[12:13], v[236:237] op_sel_hi:[1,0]
	v_pk_mul_f32 v[14:15], v[14:15], v[240:241] op_sel_hi:[1,0]
	v_pk_mul_f32 v[16:17], v[16:17], v[240:241] op_sel_hi:[1,0]
	v_pk_mul_f32 v[114:115], v[114:115], v[236:237] op_sel_hi:[1,0]
	v_pk_mul_f32 v[116:117], v[116:117], v[236:237] op_sel_hi:[1,0]
	v_pk_mul_f32 v[118:119], v[118:119], v[240:241] op_sel_hi:[1,0]
	v_pk_mul_f32 v[120:121], v[120:121], v[240:241] op_sel_hi:[1,0]
	v_pk_mul_f32 v[122:123], v[122:123], v[236:237] op_sel_hi:[1,0]
	v_pk_mul_f32 v[124:125], v[124:125], v[236:237] op_sel_hi:[1,0]
	v_pk_mul_f32 v[126:127], v[126:127], v[240:241] op_sel_hi:[1,0]
	v_pk_mul_f32 v[128:129], v[128:129], v[240:241] op_sel_hi:[1,0]
	v_pk_mul_f32 v[98:99], v[98:99], v[236:237] op_sel_hi:[1,0]
	v_pk_mul_f32 v[100:101], v[100:101], v[236:237] op_sel_hi:[1,0]
	v_pk_mul_f32 v[102:103], v[102:103], v[240:241] op_sel_hi:[1,0]
	v_pk_mul_f32 v[104:105], v[104:105], v[240:241] op_sel_hi:[1,0]
	v_pk_mul_f32 v[106:107], v[106:107], v[236:237] op_sel_hi:[1,0]
	v_pk_mul_f32 v[108:109], v[108:109], v[236:237] op_sel_hi:[1,0]
	v_pk_mul_f32 v[110:111], v[110:111], v[240:241] op_sel_hi:[1,0]
	v_pk_mul_f32 v[112:113], v[112:113], v[240:241] op_sel_hi:[1,0]
	v_pk_mul_f32 v[82:83], v[82:83], v[236:237] op_sel_hi:[1,0]
	v_pk_mul_f32 v[84:85], v[84:85], v[236:237] op_sel_hi:[1,0]
	v_pk_mul_f32 v[86:87], v[86:87], v[240:241] op_sel_hi:[1,0]
	v_pk_mul_f32 v[88:89], v[88:89], v[240:241] op_sel_hi:[1,0]
	v_pk_mul_f32 v[90:91], v[90:91], v[236:237] op_sel_hi:[1,0]
	v_pk_mul_f32 v[92:93], v[92:93], v[236:237] op_sel_hi:[1,0]
	v_pk_mul_f32 v[94:95], v[94:95], v[240:241] op_sel_hi:[1,0]
	v_pk_mul_f32 v[96:97], v[96:97], v[240:241] op_sel_hi:[1,0]
	v_pk_mul_f32 v[66:67], v[66:67], v[236:237] op_sel_hi:[1,0]
	v_pk_mul_f32 v[68:69], v[68:69], v[236:237] op_sel_hi:[1,0]
	v_pk_mul_f32 v[70:71], v[70:71], v[240:241] op_sel_hi:[1,0]
	v_pk_mul_f32 v[72:73], v[72:73], v[240:241] op_sel_hi:[1,0]
	v_pk_mul_f32 v[74:75], v[74:75], v[236:237] op_sel_hi:[1,0]
	v_pk_mul_f32 v[76:77], v[76:77], v[236:237] op_sel_hi:[1,0]
	v_pk_mul_f32 v[78:79], v[78:79], v[240:241] op_sel_hi:[1,0]
	v_pk_mul_f32 v[80:81], v[80:81], v[240:241] op_sel_hi:[1,0]
	v_pk_mul_f32 v[50:51], v[50:51], v[236:237] op_sel_hi:[1,0]
	v_pk_mul_f32 v[52:53], v[52:53], v[236:237] op_sel_hi:[1,0]
	v_pk_mul_f32 v[54:55], v[54:55], v[240:241] op_sel_hi:[1,0]
	v_pk_mul_f32 v[56:57], v[56:57], v[240:241] op_sel_hi:[1,0]
	v_pk_mul_f32 v[58:59], v[58:59], v[236:237] op_sel_hi:[1,0]
	v_pk_mul_f32 v[60:61], v[60:61], v[236:237] op_sel_hi:[1,0]
	v_pk_mul_f32 v[62:63], v[62:63], v[240:241] op_sel_hi:[1,0]
	v_pk_mul_f32 v[64:65], v[64:65], v[240:241] op_sel_hi:[1,0]
	v_pk_mul_f32 v[34:35], v[34:35], v[236:237] op_sel_hi:[1,0]
	v_pk_mul_f32 v[36:37], v[36:37], v[236:237] op_sel_hi:[1,0]
	v_pk_mul_f32 v[38:39], v[38:39], v[240:241] op_sel_hi:[1,0]
	v_pk_mul_f32 v[40:41], v[40:41], v[240:241] op_sel_hi:[1,0]
	v_pk_mul_f32 v[42:43], v[42:43], v[236:237] op_sel_hi:[1,0]
	v_pk_mul_f32 v[44:45], v[44:45], v[236:237] op_sel_hi:[1,0]
	v_pk_mul_f32 v[46:47], v[46:47], v[240:241] op_sel_hi:[1,0]
	v_pk_mul_f32 v[48:49], v[48:49], v[240:241] op_sel_hi:[1,0]
	v_pk_mul_f32 v[18:19], v[18:19], v[236:237] op_sel_hi:[1,0]
	v_pk_mul_f32 v[20:21], v[20:21], v[236:237] op_sel_hi:[1,0]
	v_pk_mul_f32 v[22:23], v[22:23], v[240:241] op_sel_hi:[1,0]
	v_pk_mul_f32 v[24:25], v[24:25], v[240:241] op_sel_hi:[1,0]
	v_pk_mul_f32 v[26:27], v[26:27], v[236:237] op_sel_hi:[1,0]
	v_pk_mul_f32 v[28:29], v[28:29], v[236:237] op_sel_hi:[1,0]
	v_pk_mul_f32 v[30:31], v[30:31], v[240:241] op_sel_hi:[1,0]
	v_pk_mul_f32 v[32:33], v[32:33], v[240:241] op_sel_hi:[1,0]
